# EpiF (GDOWN/GOUT) F-tile stores nt, on top of the nt loads
# baseline (speedup 1.0000x reference)
.LBB0_191:
	v_mov_b32_e32 v158, v160
	s_mov_b32 s40, s16
	v_mov_b32_e32 v159, v161
	s_mov_b32 s92, s23
	s_lshl_b32 s41, s48, 8
	s_lshl_b32 s48, s99, 8
	s_lshl_b32 s68, s92, 5
	s_add_i32 s68, s68, s48
	v_lshl_add_u32 v156, v159, 3, s68
	v_ashrrev_i32_e32 v157, 31, v156
	v_lshl_add_u64 v[110:111], v[156:157], 2, s[44:45]
	global_load_dwordx4 v[122:125], v[110:111], off offset:16
	global_load_dwordx4 v[126:129], v[110:111], off
	global_load_dwordx4 v[106:109], v[110:111], off offset:528
	s_nop 0
	global_load_dwordx4 v[110:113], v[110:111], off offset:512
	s_lshl_b32 s40, s40, 6
	s_add_i32 s40, s40, s41
	v_add_u32_e32 v158, s40, v158
	v_cmp_eq_u32_e32 vcc, 0, v159
	v_ashrrev_i32_e32 v159, 31, v158
	v_lshlrev_b64 v[164:165], 11, v[158:159]
	s_lshl_b32 s94, s99, 2
	s_ashr_i32 s95, s94, 31
	s_ashr_i32 s93, s92, 31
	s_waitcnt vmcnt(0)
	v_pk_mul_f32 v[166:167], v[140:141], v[124:125]
	v_pk_mul_f32 v[144:145], v[144:145], v[128:129]
	v_pk_mul_f32 v[142:143], v[142:143], v[126:127]
	v_pk_mul_f32 v[140:141], v[138:139], v[122:123]
	v_mul_f32_e32 v138, v143, v143
	v_mul_f32_e32 v139, v145, v145
	v_fmac_f32_e32 v138, v142, v142
	v_fmac_f32_e32 v139, v144, v144
	v_add_f32_e32 v138, v138, v139
	v_mul_f32_e32 v139, v141, v141
	v_fmac_f32_e32 v139, v140, v140
	v_add_f32_e32 v138, v138, v139
	v_mul_f32_e32 v139, v167, v167
	v_fmac_f32_e32 v139, v166, v166
	v_add_f32_e32 v168, v139, v138
	v_cvt_pk_bf16_f32 v138, v142, v143
	v_lshl_add_u64 v[142:143], s[62:63], 0, v[164:165]
	v_cvt_pk_bf16_f32 v139, v144, v145
	v_lshl_add_u64 v[142:143], v[156:157], 1, v[142:143]
	v_pk_mul_f32 v[136:137], v[136:137], v[112:113]
	v_pk_mul_f32 v[134:135], v[134:135], v[110:111]
	v_cvt_pk_bf16_f32 v140, v140, v141
	v_cvt_pk_bf16_f32 v141, v166, v167
	global_store_dwordx4 v[142:143], v[138:141], off nt
	s_nop 1
	v_pk_mul_f32 v[138:139], v[132:133], v[108:109]
	v_pk_mul_f32 v[132:133], v[130:131], v[106:107]
	v_mul_f32_e32 v130, v135, v135
	v_mul_f32_e32 v131, v137, v137
	v_fmac_f32_e32 v130, v134, v134
	v_fmac_f32_e32 v131, v136, v136
	v_add_f32_e32 v130, v130, v131
	v_mul_f32_e32 v131, v133, v133
	v_fmac_f32_e32 v131, v132, v132
	v_add_f32_e32 v130, v130, v131
	v_mul_f32_e32 v131, v139, v139
	v_fmac_f32_e32 v131, v138, v138
	v_add_f32_e32 v130, v131, v130
	v_cvt_pk_bf16_f32 v131, v136, v137
	v_add_f32_e32 v140, v168, v130
	v_cvt_pk_bf16_f32 v130, v134, v135
	v_cvt_pk_bf16_f32 v132, v132, v133
	v_cvt_pk_bf16_f32 v133, v138, v139
	global_store_dwordx4 v[142:143], v[130:133], off offset:256 nt
	s_nop 1
	v_and_b32_e32 v131, 64, v231
	v_xor_b32_e32 v130, 16, v231
	v_add_u32_e32 v131, 64, v131
	v_cmp_lt_i32_e64 s[40:41], v130, v131
	v_xor_b32_e32 v133, 32, v231
	s_nop 0
	v_cndmask_b32_e64 v130, v231, v130, s[40:41]
	v_lshlrev_b32_e32 v132, 2, v130
	ds_bpermute_b32 v130, v132, v140
	v_cmp_lt_i32_e64 s[40:41], v133, v131
	s_waitcnt lgkmcnt(0)
	v_add_f32_e32 v130, v140, v130
	v_cndmask_b32_e64 v131, v231, v133, s[40:41]
	v_lshlrev_b32_e32 v133, 2, v131
	ds_bpermute_b32 v131, v133, v130
	s_and_saveexec_b64 s[40:41], vcc
	s_cbranch_execz .LBB0_193
	v_lshlrev_b64 v[134:135], 6, v[158:159]
	v_lshl_add_u64 v[134:135], s[76:77], 0, v[134:135]
	v_lshl_add_u64 v[134:135], s[94:95], 2, v[134:135]
	v_lshl_add_u64 v[134:135], s[92:93], 2, v[134:135]
	s_waitcnt lgkmcnt(0)
	v_add_f32_e32 v130, v130, v131
	global_store_dword v[134:135], v130, off
.LBB0_193:
	s_or_b64 exec, exec, s[40:41]
	v_pk_mul_f32 v[120:121], v[120:121], v[128:129]
	v_pk_mul_f32 v[118:119], v[118:119], v[126:127]
	v_pk_mul_f32 v[136:137], v[116:117], v[124:125]
	v_pk_mul_f32 v[116:117], v[114:115], v[122:123]
	v_mul_f32_e32 v114, v119, v119
	v_mul_f32_e32 v115, v121, v121
	v_fmac_f32_e32 v114, v118, v118
	v_fmac_f32_e32 v115, v120, v120
	v_add_f32_e32 v114, v114, v115
	v_mul_f32_e32 v115, v117, v117
	v_fmac_f32_e32 v115, v116, v116
	v_add_f32_e32 v114, v114, v115
	v_mul_f32_e32 v115, v137, v137
	v_fmac_f32_e32 v115, v136, v136
	v_pk_mul_f32 v[104:105], v[104:105], v[112:113]
	v_pk_mul_f32 v[102:103], v[102:103], v[110:111]
	v_add_f32_e32 v138, v115, v114
	v_cvt_pk_bf16_f32 v115, v120, v121
	v_pk_mul_f32 v[120:121], v[98:99], v[106:107]
	v_mul_f32_e32 v98, v103, v103
	v_mul_f32_e32 v99, v105, v105
	v_fmac_f32_e32 v98, v102, v102
	v_fmac_f32_e32 v99, v104, v104
	v_add_f32_e32 v98, v98, v99
	v_mul_f32_e32 v99, v121, v121
	v_cvt_pk_bf16_f32 v114, v118, v119
	v_pk_mul_f32 v[118:119], v[100:101], v[108:109]
	v_fmac_f32_e32 v99, v120, v120
	v_add_f32_e32 v98, v98, v99
	v_mul_f32_e32 v99, v119, v119
	v_fmac_f32_e32 v99, v118, v118
	v_add_f32_e32 v98, v99, v98
	v_add_f32_e32 v101, v138, v98
	v_cvt_pk_bf16_f32 v116, v116, v117
	v_cvt_pk_bf16_f32 v117, v136, v137
	ds_bpermute_b32 v136, v132, v101
	v_add_u32_e32 v130, 16, v158
	s_waitcnt lgkmcnt(1)
	v_ashrrev_i32_e32 v131, 31, v130
	v_lshlrev_b64 v[134:135], 11, v[130:131]
	v_lshl_add_u64 v[98:99], s[62:63], 0, v[134:135]
	v_lshl_add_u64 v[134:135], v[156:157], 1, v[98:99]
	s_waitcnt lgkmcnt(0)
	v_add_f32_e32 v98, v101, v136
	ds_bpermute_b32 v99, v133, v98
	global_store_dwordx4 v[134:135], v[114:117], off nt
	v_cvt_pk_bf16_f32 v100, v102, v103
	v_cvt_pk_bf16_f32 v101, v104, v105
	v_cvt_pk_bf16_f32 v102, v120, v121
	v_cvt_pk_bf16_f32 v103, v118, v119
	global_store_dwordx4 v[134:135], v[100:103], off offset:256 nt
	s_and_saveexec_b64 s[40:41], vcc
	s_cbranch_execz .LBB0_195
	v_lshlrev_b64 v[100:101], 6, v[130:131]
	v_lshl_add_u64 v[100:101], s[76:77], 0, v[100:101]
	v_lshl_add_u64 v[100:101], s[94:95], 2, v[100:101]
	v_lshl_add_u64 v[100:101], s[92:93], 2, v[100:101]
	s_waitcnt lgkmcnt(0)
	v_add_f32_e32 v98, v98, v99
	global_store_dword v[100:101], v98, off
.LBB0_195:
	s_or_b64 exec, exec, s[40:41]
	v_pk_mul_f32 v[96:97], v[96:97], v[128:129]
	v_pk_mul_f32 v[94:95], v[94:95], v[126:127]
	v_pk_mul_f32 v[102:103], v[92:93], v[124:125]
	v_pk_mul_f32 v[92:93], v[90:91], v[122:123]
	v_mul_f32_e32 v90, v95, v95
	v_mul_f32_e32 v91, v97, v97
	v_fmac_f32_e32 v90, v94, v94
	v_fmac_f32_e32 v91, v96, v96
	v_add_f32_e32 v90, v90, v91
	v_mul_f32_e32 v91, v93, v93
	v_fmac_f32_e32 v91, v92, v92
	v_add_f32_e32 v90, v90, v91
	v_mul_f32_e32 v91, v103, v103
	v_fmac_f32_e32 v91, v102, v102
	v_pk_mul_f32 v[88:89], v[88:89], v[112:113]
	v_pk_mul_f32 v[86:87], v[86:87], v[110:111]
	v_add_f32_e32 v104, v91, v90
	v_cvt_pk_bf16_f32 v91, v96, v97
	v_pk_mul_f32 v[96:97], v[82:83], v[106:107]
	v_mul_f32_e32 v82, v87, v87
	v_mul_f32_e32 v83, v89, v89
	v_fmac_f32_e32 v82, v86, v86
	v_fmac_f32_e32 v83, v88, v88
	v_add_f32_e32 v82, v82, v83
	v_mul_f32_e32 v83, v97, v97
	v_cvt_pk_bf16_f32 v90, v94, v95
	v_pk_mul_f32 v[94:95], v[84:85], v[108:109]
	v_fmac_f32_e32 v83, v96, v96
	v_add_f32_e32 v82, v82, v83
	v_mul_f32_e32 v83, v95, v95
	v_fmac_f32_e32 v83, v94, v94
	v_add_f32_e32 v82, v83, v82
	v_add_f32_e32 v85, v104, v82
	v_cvt_pk_bf16_f32 v92, v92, v93
	v_cvt_pk_bf16_f32 v93, v102, v103
	ds_bpermute_b32 v102, v132, v85
	v_add_u32_e32 v98, 32, v158
	s_waitcnt lgkmcnt(1)
	v_ashrrev_i32_e32 v99, 31, v98
	v_lshlrev_b64 v[100:101], 11, v[98:99]
	v_lshl_add_u64 v[82:83], s[62:63], 0, v[100:101]
	v_lshl_add_u64 v[100:101], v[156:157], 1, v[82:83]
	s_waitcnt lgkmcnt(0)
	v_add_f32_e32 v82, v85, v102
	ds_bpermute_b32 v83, v133, v82
	global_store_dwordx4 v[100:101], v[90:93], off nt
	v_cvt_pk_bf16_f32 v84, v86, v87
	v_cvt_pk_bf16_f32 v85, v88, v89
	v_cvt_pk_bf16_f32 v86, v96, v97
	v_cvt_pk_bf16_f32 v87, v94, v95
	global_store_dwordx4 v[100:101], v[84:87], off offset:256 nt
	s_and_saveexec_b64 s[40:41], vcc
	s_cbranch_execz .LBB0_197
	v_lshlrev_b64 v[84:85], 6, v[98:99]
	v_lshl_add_u64 v[84:85], s[76:77], 0, v[84:85]
	v_lshl_add_u64 v[84:85], s[94:95], 2, v[84:85]
	v_lshl_add_u64 v[84:85], s[92:93], 2, v[84:85]
	s_waitcnt lgkmcnt(0)
	v_add_f32_e32 v82, v82, v83
	global_store_dword v[84:85], v82, off
.LBB0_197:
	s_or_b64 exec, exec, s[40:41]
	v_pk_mul_f32 v[80:81], v[80:81], v[128:129]
	v_pk_mul_f32 v[78:79], v[78:79], v[126:127]
	v_pk_mul_f32 v[86:87], v[76:77], v[124:125]
	v_pk_mul_f32 v[76:77], v[74:75], v[122:123]
	v_mul_f32_e32 v74, v79, v79
	v_mul_f32_e32 v75, v81, v81
	v_fmac_f32_e32 v74, v78, v78
	v_fmac_f32_e32 v75, v80, v80
	v_add_f32_e32 v74, v74, v75
	v_mul_f32_e32 v75, v77, v77
	v_fmac_f32_e32 v75, v76, v76
	v_add_f32_e32 v74, v74, v75
	v_mul_f32_e32 v75, v87, v87
	v_fmac_f32_e32 v75, v86, v86
	v_pk_mul_f32 v[72:73], v[72:73], v[112:113]
	v_pk_mul_f32 v[70:71], v[70:71], v[110:111]
	v_add_f32_e32 v88, v75, v74
	v_cvt_pk_bf16_f32 v75, v80, v81
	v_pk_mul_f32 v[80:81], v[66:67], v[106:107]
	v_mul_f32_e32 v66, v71, v71
	v_mul_f32_e32 v67, v73, v73
	v_fmac_f32_e32 v66, v70, v70
	v_fmac_f32_e32 v67, v72, v72
	v_add_f32_e32 v66, v66, v67
	v_mul_f32_e32 v67, v81, v81
	v_cvt_pk_bf16_f32 v74, v78, v79
	v_pk_mul_f32 v[78:79], v[68:69], v[108:109]
	v_fmac_f32_e32 v67, v80, v80
	v_add_f32_e32 v66, v66, v67
	v_mul_f32_e32 v67, v79, v79
	v_fmac_f32_e32 v67, v78, v78
	v_add_f32_e32 v66, v67, v66
	v_add_f32_e32 v69, v88, v66
	v_cvt_pk_bf16_f32 v76, v76, v77
	v_cvt_pk_bf16_f32 v77, v86, v87
	ds_bpermute_b32 v86, v132, v69
	v_add_u32_e32 v82, 48, v158
	s_waitcnt lgkmcnt(1)
	v_ashrrev_i32_e32 v83, 31, v82
	v_lshlrev_b64 v[84:85], 11, v[82:83]
	v_lshl_add_u64 v[66:67], s[62:63], 0, v[84:85]
	v_lshl_add_u64 v[84:85], v[156:157], 1, v[66:67]
	s_waitcnt lgkmcnt(0)
	v_add_f32_e32 v66, v69, v86
	ds_bpermute_b32 v67, v133, v66
	global_store_dwordx4 v[84:85], v[74:77], off nt
	v_cvt_pk_bf16_f32 v68, v70, v71
	v_cvt_pk_bf16_f32 v69, v72, v73
	v_cvt_pk_bf16_f32 v70, v80, v81
	v_cvt_pk_bf16_f32 v71, v78, v79
	global_store_dwordx4 v[84:85], v[68:71], off offset:256 nt
	s_and_saveexec_b64 s[40:41], vcc
	s_cbranch_execz .LBB0_199
	v_lshlrev_b64 v[68:69], 6, v[82:83]
	v_lshl_add_u64 v[68:69], s[76:77], 0, v[68:69]
	v_lshl_add_u64 v[68:69], s[94:95], 2, v[68:69]
	v_lshl_add_u64 v[68:69], s[92:93], 2, v[68:69]
	s_waitcnt lgkmcnt(0)
	v_add_f32_e32 v66, v66, v67
	global_store_dword v[68:69], v66, off
.LBB0_199:
	s_or_b64 exec, exec, s[40:41]
	v_pk_mul_f32 v[64:65], v[64:65], v[128:129]
	v_pk_mul_f32 v[62:63], v[62:63], v[126:127]
	v_pk_mul_f32 v[70:71], v[60:61], v[124:125]
	v_pk_mul_f32 v[60:61], v[58:59], v[122:123]
	v_mul_f32_e32 v58, v63, v63
	v_mul_f32_e32 v59, v65, v65
	v_fmac_f32_e32 v58, v62, v62
	v_fmac_f32_e32 v59, v64, v64
	v_add_f32_e32 v58, v58, v59
	v_mul_f32_e32 v59, v61, v61
	v_fmac_f32_e32 v59, v60, v60
	v_add_f32_e32 v58, v58, v59
	v_mul_f32_e32 v59, v71, v71
	v_fmac_f32_e32 v59, v70, v70
	v_pk_mul_f32 v[56:57], v[56:57], v[112:113]
	v_pk_mul_f32 v[54:55], v[54:55], v[110:111]
	v_add_f32_e32 v72, v59, v58
	v_cvt_pk_bf16_f32 v59, v64, v65
	v_pk_mul_f32 v[64:65], v[50:51], v[106:107]
	v_mul_f32_e32 v50, v55, v55
	v_mul_f32_e32 v51, v57, v57
	v_fmac_f32_e32 v50, v54, v54
	v_fmac_f32_e32 v51, v56, v56
	v_add_f32_e32 v50, v50, v51
	v_mul_f32_e32 v51, v65, v65
	v_cvt_pk_bf16_f32 v58, v62, v63
	v_pk_mul_f32 v[62:63], v[52:53], v[108:109]
	v_fmac_f32_e32 v51, v64, v64
	v_add_f32_e32 v50, v50, v51
	v_mul_f32_e32 v51, v63, v63
	v_fmac_f32_e32 v51, v62, v62
	v_add_f32_e32 v50, v51, v50
	v_add_f32_e32 v53, v72, v50
	v_cvt_pk_bf16_f32 v60, v60, v61
	v_cvt_pk_bf16_f32 v61, v70, v71
	ds_bpermute_b32 v70, v132, v53
	v_add_u32_e32 v66, 0x80, v158
	s_waitcnt lgkmcnt(1)
	v_ashrrev_i32_e32 v67, 31, v66
	v_lshlrev_b64 v[68:69], 11, v[66:67]
	v_lshl_add_u64 v[50:51], s[62:63], 0, v[68:69]
	v_lshl_add_u64 v[68:69], v[156:157], 1, v[50:51]
	s_waitcnt lgkmcnt(0)
	v_add_f32_e32 v50, v53, v70
	ds_bpermute_b32 v51, v133, v50
	global_store_dwordx4 v[68:69], v[58:61], off nt
	v_cvt_pk_bf16_f32 v52, v54, v55
	v_cvt_pk_bf16_f32 v53, v56, v57
	v_cvt_pk_bf16_f32 v54, v64, v65
	v_cvt_pk_bf16_f32 v55, v62, v63
	global_store_dwordx4 v[68:69], v[52:55], off offset:256 nt
	s_and_saveexec_b64 s[40:41], vcc
	s_cbranch_execz .LBB0_201
	v_lshlrev_b64 v[52:53], 6, v[66:67]
	v_lshl_add_u64 v[52:53], s[76:77], 0, v[52:53]
	v_lshl_add_u64 v[52:53], s[94:95], 2, v[52:53]
	v_lshl_add_u64 v[52:53], s[92:93], 2, v[52:53]
	s_waitcnt lgkmcnt(0)
	v_add_f32_e32 v50, v50, v51
	global_store_dword v[52:53], v50, off
.LBB0_201:
	s_or_b64 exec, exec, s[40:41]
	v_pk_mul_f32 v[48:49], v[48:49], v[128:129]
	v_pk_mul_f32 v[46:47], v[46:47], v[126:127]
	v_pk_mul_f32 v[54:55], v[44:45], v[124:125]
	v_pk_mul_f32 v[44:45], v[42:43], v[122:123]
	v_mul_f32_e32 v42, v47, v47
	v_mul_f32_e32 v43, v49, v49
	v_fmac_f32_e32 v42, v46, v46
	v_fmac_f32_e32 v43, v48, v48
	v_add_f32_e32 v42, v42, v43
	v_mul_f32_e32 v43, v45, v45
	v_fmac_f32_e32 v43, v44, v44
	v_add_f32_e32 v42, v42, v43
	v_mul_f32_e32 v43, v55, v55
	v_fmac_f32_e32 v43, v54, v54
	v_pk_mul_f32 v[40:41], v[40:41], v[112:113]
	v_pk_mul_f32 v[38:39], v[38:39], v[110:111]
	v_add_f32_e32 v56, v43, v42
	v_cvt_pk_bf16_f32 v43, v48, v49
	v_pk_mul_f32 v[48:49], v[34:35], v[106:107]
	v_mul_f32_e32 v34, v39, v39
	v_mul_f32_e32 v35, v41, v41
	v_fmac_f32_e32 v34, v38, v38
	v_fmac_f32_e32 v35, v40, v40
	v_add_f32_e32 v34, v34, v35
	v_mul_f32_e32 v35, v49, v49
	v_cvt_pk_bf16_f32 v42, v46, v47
	v_pk_mul_f32 v[46:47], v[36:37], v[108:109]
	v_fmac_f32_e32 v35, v48, v48
	v_add_f32_e32 v34, v34, v35
	v_mul_f32_e32 v35, v47, v47
	v_fmac_f32_e32 v35, v46, v46
	v_add_f32_e32 v34, v35, v34
	v_add_f32_e32 v37, v56, v34
	v_cvt_pk_bf16_f32 v44, v44, v45
	v_cvt_pk_bf16_f32 v45, v54, v55
	ds_bpermute_b32 v54, v132, v37
	v_add_u32_e32 v50, 0x90, v158
	s_waitcnt lgkmcnt(1)
	v_ashrrev_i32_e32 v51, 31, v50
	v_lshlrev_b64 v[52:53], 11, v[50:51]
	v_lshl_add_u64 v[34:35], s[62:63], 0, v[52:53]
	v_lshl_add_u64 v[52:53], v[156:157], 1, v[34:35]
	s_waitcnt lgkmcnt(0)
	v_add_f32_e32 v34, v37, v54
	ds_bpermute_b32 v35, v133, v34
	global_store_dwordx4 v[52:53], v[42:45], off nt
	v_cvt_pk_bf16_f32 v36, v38, v39
	v_cvt_pk_bf16_f32 v37, v40, v41
	v_cvt_pk_bf16_f32 v38, v48, v49
	v_cvt_pk_bf16_f32 v39, v46, v47
	global_store_dwordx4 v[52:53], v[36:39], off offset:256 nt
	s_and_saveexec_b64 s[40:41], vcc
	s_cbranch_execz .LBB0_203
	v_lshlrev_b64 v[36:37], 6, v[50:51]
	v_lshl_add_u64 v[36:37], s[76:77], 0, v[36:37]
	v_lshl_add_u64 v[36:37], s[94:95], 2, v[36:37]
	v_lshl_add_u64 v[36:37], s[92:93], 2, v[36:37]
	s_waitcnt lgkmcnt(0)
	v_add_f32_e32 v34, v34, v35
	global_store_dword v[36:37], v34, off
.LBB0_203:
	s_or_b64 exec, exec, s[40:41]
	v_pk_mul_f32 v[32:33], v[32:33], v[128:129]
	v_pk_mul_f32 v[30:31], v[30:31], v[126:127]
	v_pk_mul_f32 v[38:39], v[28:29], v[124:125]
	v_pk_mul_f32 v[28:29], v[26:27], v[122:123]
	v_mul_f32_e32 v26, v31, v31
	v_mul_f32_e32 v27, v33, v33
	v_fmac_f32_e32 v26, v30, v30
	v_fmac_f32_e32 v27, v32, v32
	v_add_f32_e32 v26, v26, v27
	v_mul_f32_e32 v27, v29, v29
	v_fmac_f32_e32 v27, v28, v28
	v_add_f32_e32 v26, v26, v27
	v_mul_f32_e32 v27, v39, v39
	v_fmac_f32_e32 v27, v38, v38
	v_pk_mul_f32 v[24:25], v[24:25], v[112:113]
	v_pk_mul_f32 v[22:23], v[22:23], v[110:111]
	v_add_f32_e32 v40, v27, v26
	v_cvt_pk_bf16_f32 v27, v32, v33
	v_pk_mul_f32 v[32:33], v[18:19], v[106:107]
	v_mul_f32_e32 v18, v23, v23
	v_mul_f32_e32 v19, v25, v25
	v_fmac_f32_e32 v18, v22, v22
	v_fmac_f32_e32 v19, v24, v24
	v_add_f32_e32 v18, v18, v19
	v_mul_f32_e32 v19, v33, v33
	v_cvt_pk_bf16_f32 v26, v30, v31
	v_pk_mul_f32 v[30:31], v[20:21], v[108:109]
	v_fmac_f32_e32 v19, v32, v32
	v_add_f32_e32 v18, v18, v19
	v_mul_f32_e32 v19, v31, v31
	v_fmac_f32_e32 v19, v30, v30
	v_add_f32_e32 v18, v19, v18
	v_add_f32_e32 v21, v40, v18
	v_cvt_pk_bf16_f32 v28, v28, v29
	v_cvt_pk_bf16_f32 v29, v38, v39
	ds_bpermute_b32 v38, v132, v21
	v_add_u32_e32 v34, 0xa0, v158
	s_waitcnt lgkmcnt(1)
	v_ashrrev_i32_e32 v35, 31, v34
	v_lshlrev_b64 v[36:37], 11, v[34:35]
	v_lshl_add_u64 v[18:19], s[62:63], 0, v[36:37]
	v_lshl_add_u64 v[36:37], v[156:157], 1, v[18:19]
	s_waitcnt lgkmcnt(0)
	v_add_f32_e32 v18, v21, v38
	ds_bpermute_b32 v19, v133, v18
	global_store_dwordx4 v[36:37], v[26:29], off nt
	v_cvt_pk_bf16_f32 v20, v22, v23
	v_cvt_pk_bf16_f32 v21, v24, v25
	v_cvt_pk_bf16_f32 v22, v32, v33
	v_cvt_pk_bf16_f32 v23, v30, v31
	global_store_dwordx4 v[36:37], v[20:23], off offset:256 nt
	s_and_saveexec_b64 s[40:41], vcc
	s_cbranch_execz .LBB0_205
	v_lshlrev_b64 v[20:21], 6, v[34:35]
	v_lshl_add_u64 v[20:21], s[76:77], 0, v[20:21]
	v_lshl_add_u64 v[20:21], s[94:95], 2, v[20:21]
	v_lshl_add_u64 v[20:21], s[92:93], 2, v[20:21]
	s_waitcnt lgkmcnt(0)
	v_add_f32_e32 v18, v18, v19
	global_store_dword v[20:21], v18, off
.LBB0_205:
	s_or_b64 exec, exec, s[40:41]
	v_pk_mul_f32 v[16:17], v[16:17], v[128:129]
	v_pk_mul_f32 v[14:15], v[14:15], v[126:127]
	v_pk_mul_f32 v[22:23], v[12:13], v[124:125]
	v_pk_mul_f32 v[12:13], v[10:11], v[122:123]
	v_mul_f32_e32 v10, v15, v15
	v_mul_f32_e32 v11, v17, v17
	v_fmac_f32_e32 v10, v14, v14
	v_fmac_f32_e32 v11, v16, v16
	v_add_f32_e32 v10, v10, v11
	v_mul_f32_e32 v11, v13, v13
	v_fmac_f32_e32 v11, v12, v12
	v_add_f32_e32 v10, v10, v11
	v_mul_f32_e32 v11, v23, v23
	v_fmac_f32_e32 v11, v22, v22
	v_pk_mul_f32 v[8:9], v[8:9], v[112:113]
	v_pk_mul_f32 v[6:7], v[6:7], v[110:111]
	v_add_f32_e32 v24, v11, v10
	v_cvt_pk_bf16_f32 v11, v16, v17
	v_pk_mul_f32 v[16:17], v[2:3], v[106:107]
	v_mul_f32_e32 v2, v7, v7
	v_mul_f32_e32 v3, v9, v9
	v_fmac_f32_e32 v2, v6, v6
	v_fmac_f32_e32 v3, v8, v8
	v_add_f32_e32 v2, v2, v3
	v_mul_f32_e32 v3, v17, v17
	v_cvt_pk_bf16_f32 v10, v14, v15
	v_pk_mul_f32 v[14:15], v[4:5], v[108:109]
	v_fmac_f32_e32 v3, v16, v16
	v_add_f32_e32 v2, v2, v3
	v_mul_f32_e32 v3, v15, v15
	v_fmac_f32_e32 v3, v14, v14
	v_add_f32_e32 v2, v3, v2
	v_add_f32_e32 v5, v24, v2
	v_cvt_pk_bf16_f32 v12, v12, v13
	v_cvt_pk_bf16_f32 v13, v22, v23
	ds_bpermute_b32 v22, v132, v5
	v_add_u32_e32 v18, 0xb0, v158
	s_waitcnt lgkmcnt(1)
	v_ashrrev_i32_e32 v19, 31, v18
	v_lshlrev_b64 v[20:21], 11, v[18:19]
	v_lshl_add_u64 v[2:3], s[62:63], 0, v[20:21]
	v_lshl_add_u64 v[20:21], v[156:157], 1, v[2:3]
	s_waitcnt lgkmcnt(0)
	v_add_f32_e32 v2, v5, v22
	ds_bpermute_b32 v3, v133, v2
	global_store_dwordx4 v[20:21], v[10:13], off nt
	v_cvt_pk_bf16_f32 v4, v6, v7
	v_cvt_pk_bf16_f32 v5, v8, v9
	v_cvt_pk_bf16_f32 v6, v16, v17
	v_cvt_pk_bf16_f32 v7, v14, v15
	global_store_dwordx4 v[20:21], v[4:7], off offset:256 nt
	s_and_saveexec_b64 s[40:41], vcc
	s_cbranch_execz .LBB0_207
	v_lshlrev_b64 v[4:5], 6, v[18:19]
	v_lshl_add_u64 v[4:5], s[76:77], 0, v[4:5]
	v_lshl_add_u64 v[4:5], s[94:95], 2, v[4:5]
	v_lshl_add_u64 v[4:5], s[92:93], 2, v[4:5]
	s_waitcnt lgkmcnt(0)
	v_add_f32_e32 v2, v2, v3
	global_store_dword v[4:5], v2, off
